# stick-breaking vote through LDS ds ops instead of flat ops
# speedup vs baseline: 1.0526x; 1.0070x over previous
; template <int MODE>
; DI void attn_item(const CP& p, int l, int b, int head, int qt, char* smem) {
;     ...
;   if (MODE != 1) { if (tid < 3) sVote[tid] = 0u; }
.LBB0_440:
	s_andn2_b64 vcc, exec, s[4:5]
	s_cbranch_vccnz .LBB0_464
	v_mov_b32_e32 v0, v202
	s_nop 0
	v_cmp_gt_i32_e32 vcc, 3, v0
	s_and_saveexec_b64 s[4:5], vcc
	s_cbranch_execz .LBB0_443
	s_waitcnt lgkmcnt(0)
	v_lshl_add_u32 v1, v0, 2, 0
	v_add_u32_e32 v2, 0x9800, v1
	ds_write_b32 v2, v33

; template <int MODE>
; DI void attn_item(const CP& p, int l, int b, int head, int qt, char* smem) {
;     ...
;       if (cont) sVote[vit] = 1u;
;       wdone = __builtin_amdgcn_ballot_w64(cont) == 0ull;
;       const int vnx = vit == 2 ? 0 : vit + 1;
;       if (tid == 0) sVote[vnx] = 0u;
;       __syncthreads();
;       if (sVote[vit] == 0u) break;
;       vit = vnx;
;     } else {
;       __syncthreads();
;     }
;     buf ^= 1;
.LBB0_454:
	s_lshl_b32 s8, s81, 2
	s_add_i32 s8, s8, 0x9800
	v_mov_b32_e32 v34, s8
	ds_write_b32 v34, v206
.LBB0_455:
	s_or_b64 exec, exec, s[10:11]
	s_add_i32 s8, s81, 1
	v_cndmask_b32_e64 v32, 0, 1, vcc
	s_cmp_lg_u32 s81, 2
	v_cmp_ne_u32_e32 vcc, 0, v32
	s_cselect_b32 s74, s8, 0
	s_and_saveexec_b64 s[10:11], s[6:7]
	s_cbranch_execz .LBB0_457
	s_lshl_b32 s8, s74, 2
	s_add_i32 s8, s8, 0x9800
	v_mov_b32_e32 v34, s8
	ds_write_b32 v34, v33
.LBB0_457:
	s_or_b64 exec, exec, s[10:11]
	s_lshl_b32 s8, s81, 2
	s_add_i32 s8, s8, 0x9800
	v_mov_b32_e32 v34, s8
	s_waitcnt lgkmcnt(0)
	s_barrier
	ds_read_b32 v32, v34
	s_mov_b64 s[14:15], -1
	s_waitcnt lgkmcnt(0)
	v_cmp_ne_u32_e64 s[10:11], 0, v32
	s_and_saveexec_b64 s[16:17], s[10:11]
	s_cbranch_execz .LBB0_444
	s_cmp_eq_u64 vcc, 0
	s_cselect_b64 s[12:13], -1, 0
	s_xor_b32 s90, s90, 1
	s_sub_i32 s48, s48, 64
	s_add_i32 s80, s80, -1
	s_cmp_eq_u32 s80, 0
	s_cselect_b64 s[10:11], -1, 0
	s_orn2_b64 s[14:15], s[10:11], exec
	s_branch .LBB0_444
